# adds: nt hint on the GU epilogue's HID stores (read once by the Down GEMM)
# speedup vs baseline: 1.0094x; 1.0023x over previous
.LBB0_290:
	s_mov_b64 s[22:23], -1
	s_and_b64 vcc, exec, s[0:1]
	v_lshl_add_u32 v149, s11, 8, v1
	v_lshl_or_b32 v144, s10, 7, v147
	v_ashrrev_i32_e32 v145, 31, v144
	v_mov_b64_e32 v[142:143], s[34:35]
	v_lshlrev_b64 v[144:145], 1, v[144:145]
	v_mad_i64_i32 v[214:215], s[10:11], v149, s87, v[142:143]
	v_or_b32_e32 v216, 16, v149
	v_mad_i64_i32 v[216:217], s[10:11], v216, s87, v[142:143]
	v_or_b32_e32 v218, 32, v149
	v_mad_i64_i32 v[218:219], s[10:11], v218, s87, v[142:143]
	v_or_b32_e32 v220, 48, v149
	v_mad_i64_i32 v[220:221], s[10:11], v220, s87, v[142:143]
	v_add_u32_e32 v222, 0x80, v149
	v_mad_i64_i32 v[222:223], s[10:11], v222, s87, v[142:143]
	v_add_u32_e32 v224, 0x90, v149
	v_mad_i64_i32 v[224:225], s[10:11], v224, s87, v[142:143]
	v_add_u32_e32 v226, 0xa0, v149
	v_mad_i64_i32 v[226:227], s[10:11], v226, s87, v[142:143]
	v_add_u32_e32 v236, 0xb0, v149
	v_mad_i64_i32 v[236:237], s[10:11], v236, s87, v[142:143]
	v_lshl_add_u64 v[214:215], v[214:215], 0, v[144:145]
	v_lshl_add_u64 v[216:217], v[216:217], 0, v[144:145]
	v_lshl_add_u64 v[218:219], v[218:219], 0, v[144:145]
	v_lshl_add_u64 v[220:221], v[220:221], 0, v[144:145]
	v_lshl_add_u64 v[222:223], v[222:223], 0, v[144:145]
	v_lshl_add_u64 v[224:225], v[224:225], 0, v[144:145]
	v_lshl_add_u64 v[226:227], v[226:227], 0, v[144:145]
	v_lshl_add_u64 v[236:237], v[236:237], 0, v[144:145]
	v_mul_f32_e32 v150, 0xbfb8aa3b, v122
	v_mul_f32_e32 v152, 0xbfb8aa3b, v124
	v_mul_f32_e32 v151, 0xbfb8aa3b, v123
	v_mul_f32_e32 v153, 0xbfb8aa3b, v125
	v_exp_f32_e32 v150, v150
	v_exp_f32_e32 v152, v152
	v_exp_f32_e32 v151, v151
	v_exp_f32_e32 v153, v153
	v_add_f32_e32 v150, 1.0, v150
	v_add_f32_e32 v152, 1.0, v152
	v_add_f32_e32 v151, 1.0, v151
	v_add_f32_e32 v153, 1.0, v153
	v_rcp_f32_e32 v150, v150
	v_rcp_f32_e32 v152, v152
	v_rcp_f32_e32 v151, v151
	v_rcp_f32_e32 v153, v153
	v_pk_mul_f32 v[122:123], v[122:123], v[150:151]
	v_pk_mul_f32 v[124:125], v[124:125], v[152:153]
	v_pk_mul_f32 v[122:123], v[126:127], v[122:123]
	v_pk_mul_f32 v[124:125], v[128:129], v[124:125]
	v_cvt_pk_bf16_f32 v160, v122, v123
	v_cvt_pk_bf16_f32 v161, v124, v125
	v_mul_f32_e32 v154, 0xbfb8aa3b, v118
	v_mul_f32_e32 v156, 0xbfb8aa3b, v120
	v_mul_f32_e32 v155, 0xbfb8aa3b, v119
	v_mul_f32_e32 v157, 0xbfb8aa3b, v121
	v_exp_f32_e32 v154, v154
	v_exp_f32_e32 v156, v156
	v_exp_f32_e32 v155, v155
	v_exp_f32_e32 v157, v157
	v_add_f32_e32 v154, 1.0, v154
	v_add_f32_e32 v156, 1.0, v156
	v_add_f32_e32 v155, 1.0, v155
	v_add_f32_e32 v157, 1.0, v157
	v_rcp_f32_e32 v154, v154
	v_rcp_f32_e32 v156, v156
	v_rcp_f32_e32 v155, v155
	v_rcp_f32_e32 v157, v157
	v_pk_mul_f32 v[118:119], v[118:119], v[154:155]
	v_pk_mul_f32 v[120:121], v[120:121], v[156:157]
	v_pk_mul_f32 v[118:119], v[114:115], v[118:119]
	v_pk_mul_f32 v[120:121], v[116:117], v[120:121]
	v_cvt_pk_bf16_f32 v162, v118, v119
	v_cvt_pk_bf16_f32 v163, v120, v121
	global_store_dwordx4 v[214:215], v[160:163], off nt
	v_mul_f32_e32 v150, 0xbfb8aa3b, v110
	v_mul_f32_e32 v152, 0xbfb8aa3b, v112
	v_mul_f32_e32 v151, 0xbfb8aa3b, v111
	v_mul_f32_e32 v153, 0xbfb8aa3b, v113
	v_exp_f32_e32 v150, v150
	v_exp_f32_e32 v152, v152
	v_exp_f32_e32 v151, v151
	v_exp_f32_e32 v153, v153
	v_add_f32_e32 v150, 1.0, v150
	v_add_f32_e32 v152, 1.0, v152
	v_add_f32_e32 v151, 1.0, v151
	v_add_f32_e32 v153, 1.0, v153
	v_rcp_f32_e32 v150, v150
	v_rcp_f32_e32 v152, v152
	v_rcp_f32_e32 v151, v151
	v_rcp_f32_e32 v153, v153
	v_pk_mul_f32 v[110:111], v[110:111], v[150:151]
	v_pk_mul_f32 v[112:113], v[112:113], v[152:153]
	v_pk_mul_f32 v[110:111], v[106:107], v[110:111]
	v_pk_mul_f32 v[112:113], v[108:109], v[112:113]
	v_cvt_pk_bf16_f32 v164, v110, v111
	v_cvt_pk_bf16_f32 v165, v112, v113
	v_mul_f32_e32 v154, 0xbfb8aa3b, v102
	v_mul_f32_e32 v156, 0xbfb8aa3b, v104
	v_mul_f32_e32 v155, 0xbfb8aa3b, v103
	v_mul_f32_e32 v157, 0xbfb8aa3b, v105
	v_exp_f32_e32 v154, v154
	v_exp_f32_e32 v156, v156
	v_exp_f32_e32 v155, v155
	v_exp_f32_e32 v157, v157
	v_add_f32_e32 v154, 1.0, v154
	v_add_f32_e32 v156, 1.0, v156
	v_add_f32_e32 v155, 1.0, v155
	v_add_f32_e32 v157, 1.0, v157
	v_rcp_f32_e32 v154, v154
	v_rcp_f32_e32 v156, v156
	v_rcp_f32_e32 v155, v155
	v_rcp_f32_e32 v157, v157
	v_pk_mul_f32 v[102:103], v[102:103], v[154:155]
	v_pk_mul_f32 v[104:105], v[104:105], v[156:157]
	v_pk_mul_f32 v[102:103], v[98:99], v[102:103]
	v_pk_mul_f32 v[104:105], v[100:101], v[104:105]
	v_cvt_pk_bf16_f32 v166, v102, v103
	v_cvt_pk_bf16_f32 v167, v104, v105
	global_store_dwordx4 v[216:217], v[164:167], off nt
	v_mul_f32_e32 v150, 0xbfb8aa3b, v94
	v_mul_f32_e32 v152, 0xbfb8aa3b, v96
	v_mul_f32_e32 v151, 0xbfb8aa3b, v95
	v_mul_f32_e32 v153, 0xbfb8aa3b, v97
	v_exp_f32_e32 v150, v150
	v_exp_f32_e32 v152, v152
	v_exp_f32_e32 v151, v151
	v_exp_f32_e32 v153, v153
	v_add_f32_e32 v150, 1.0, v150
	v_add_f32_e32 v152, 1.0, v152
	v_add_f32_e32 v151, 1.0, v151
	v_add_f32_e32 v153, 1.0, v153
	v_rcp_f32_e32 v150, v150
	v_rcp_f32_e32 v152, v152
	v_rcp_f32_e32 v151, v151
	v_rcp_f32_e32 v153, v153
	v_pk_mul_f32 v[94:95], v[94:95], v[150:151]
	v_pk_mul_f32 v[96:97], v[96:97], v[152:153]
	v_pk_mul_f32 v[94:95], v[90:91], v[94:95]
	v_pk_mul_f32 v[96:97], v[92:93], v[96:97]
	v_cvt_pk_bf16_f32 v168, v94, v95
	v_cvt_pk_bf16_f32 v169, v96, v97
	v_mul_f32_e32 v154, 0xbfb8aa3b, v86
	v_mul_f32_e32 v156, 0xbfb8aa3b, v88
	v_mul_f32_e32 v155, 0xbfb8aa3b, v87
	v_mul_f32_e32 v157, 0xbfb8aa3b, v89
	v_exp_f32_e32 v154, v154
	v_exp_f32_e32 v156, v156
	v_exp_f32_e32 v155, v155
	v_exp_f32_e32 v157, v157
	v_add_f32_e32 v154, 1.0, v154
	v_add_f32_e32 v156, 1.0, v156
	v_add_f32_e32 v155, 1.0, v155
	v_add_f32_e32 v157, 1.0, v157
	v_rcp_f32_e32 v154, v154
	v_rcp_f32_e32 v156, v156
	v_rcp_f32_e32 v155, v155
	v_rcp_f32_e32 v157, v157
	v_pk_mul_f32 v[86:87], v[86:87], v[154:155]
	v_pk_mul_f32 v[88:89], v[88:89], v[156:157]
	v_pk_mul_f32 v[86:87], v[82:83], v[86:87]
	v_pk_mul_f32 v[88:89], v[84:85], v[88:89]
	v_cvt_pk_bf16_f32 v170, v86, v87
	v_cvt_pk_bf16_f32 v171, v88, v89
	global_store_dwordx4 v[218:219], v[168:171], off nt
	v_mul_f32_e32 v150, 0xbfb8aa3b, v78
	v_mul_f32_e32 v152, 0xbfb8aa3b, v80
	v_mul_f32_e32 v151, 0xbfb8aa3b, v79
	v_mul_f32_e32 v153, 0xbfb8aa3b, v81
	v_exp_f32_e32 v150, v150
	v_exp_f32_e32 v152, v152
	v_exp_f32_e32 v151, v151
	v_exp_f32_e32 v153, v153
	v_add_f32_e32 v150, 1.0, v150
	v_add_f32_e32 v152, 1.0, v152
	v_add_f32_e32 v151, 1.0, v151
	v_add_f32_e32 v153, 1.0, v153
	v_rcp_f32_e32 v150, v150
	v_rcp_f32_e32 v152, v152
	v_rcp_f32_e32 v151, v151
	v_rcp_f32_e32 v153, v153
	v_pk_mul_f32 v[78:79], v[78:79], v[150:151]
	v_pk_mul_f32 v[80:81], v[80:81], v[152:153]
	v_pk_mul_f32 v[78:79], v[74:75], v[78:79]
	v_pk_mul_f32 v[80:81], v[76:77], v[80:81]
	v_cvt_pk_bf16_f32 v172, v78, v79
	v_cvt_pk_bf16_f32 v173, v80, v81
	v_mul_f32_e32 v154, 0xbfb8aa3b, v70
	v_mul_f32_e32 v156, 0xbfb8aa3b, v72
	v_mul_f32_e32 v155, 0xbfb8aa3b, v71
	v_mul_f32_e32 v157, 0xbfb8aa3b, v73
	v_exp_f32_e32 v154, v154
	v_exp_f32_e32 v156, v156
	v_exp_f32_e32 v155, v155
	v_exp_f32_e32 v157, v157
	v_add_f32_e32 v154, 1.0, v154
	v_add_f32_e32 v156, 1.0, v156
	v_add_f32_e32 v155, 1.0, v155
	v_add_f32_e32 v157, 1.0, v157
	v_rcp_f32_e32 v154, v154
	v_rcp_f32_e32 v156, v156
	v_rcp_f32_e32 v155, v155
	v_rcp_f32_e32 v157, v157
	v_pk_mul_f32 v[70:71], v[70:71], v[154:155]
	v_pk_mul_f32 v[72:73], v[72:73], v[156:157]
	v_pk_mul_f32 v[70:71], v[66:67], v[70:71]
	v_pk_mul_f32 v[72:73], v[68:69], v[72:73]
	v_cvt_pk_bf16_f32 v174, v70, v71
	v_cvt_pk_bf16_f32 v175, v72, v73
	global_store_dwordx4 v[220:221], v[172:175], off nt
	v_mul_f32_e32 v150, 0xbfb8aa3b, v62
	v_mul_f32_e32 v152, 0xbfb8aa3b, v64
	v_mul_f32_e32 v151, 0xbfb8aa3b, v63
	v_mul_f32_e32 v153, 0xbfb8aa3b, v65
	v_exp_f32_e32 v150, v150
	v_exp_f32_e32 v152, v152
	v_exp_f32_e32 v151, v151
	v_exp_f32_e32 v153, v153
	v_add_f32_e32 v150, 1.0, v150
	v_add_f32_e32 v152, 1.0, v152
	v_add_f32_e32 v151, 1.0, v151
	v_add_f32_e32 v153, 1.0, v153
	v_rcp_f32_e32 v150, v150
	v_rcp_f32_e32 v152, v152
	v_rcp_f32_e32 v151, v151
	v_rcp_f32_e32 v153, v153
	v_pk_mul_f32 v[62:63], v[62:63], v[150:151]
	v_pk_mul_f32 v[64:65], v[64:65], v[152:153]
	v_pk_mul_f32 v[62:63], v[58:59], v[62:63]
	v_pk_mul_f32 v[64:65], v[60:61], v[64:65]
	v_cvt_pk_bf16_f32 v176, v62, v63
	v_cvt_pk_bf16_f32 v177, v64, v65
	v_mul_f32_e32 v154, 0xbfb8aa3b, v54
	v_mul_f32_e32 v156, 0xbfb8aa3b, v56
	v_mul_f32_e32 v155, 0xbfb8aa3b, v55
	v_mul_f32_e32 v157, 0xbfb8aa3b, v57
	v_exp_f32_e32 v154, v154
	v_exp_f32_e32 v156, v156
	v_exp_f32_e32 v155, v155
	v_exp_f32_e32 v157, v157
	v_add_f32_e32 v154, 1.0, v154
	v_add_f32_e32 v156, 1.0, v156
	v_add_f32_e32 v155, 1.0, v155
	v_add_f32_e32 v157, 1.0, v157
	v_rcp_f32_e32 v154, v154
	v_rcp_f32_e32 v156, v156
	v_rcp_f32_e32 v155, v155
	v_rcp_f32_e32 v157, v157
	v_pk_mul_f32 v[54:55], v[54:55], v[154:155]
	v_pk_mul_f32 v[56:57], v[56:57], v[156:157]
	v_pk_mul_f32 v[54:55], v[50:51], v[54:55]
	v_pk_mul_f32 v[56:57], v[52:53], v[56:57]
	v_cvt_pk_bf16_f32 v178, v54, v55
	v_cvt_pk_bf16_f32 v179, v56, v57
	global_store_dwordx4 v[222:223], v[176:179], off nt
	v_mul_f32_e32 v150, 0xbfb8aa3b, v46
	v_mul_f32_e32 v152, 0xbfb8aa3b, v48
	v_mul_f32_e32 v151, 0xbfb8aa3b, v47
	v_mul_f32_e32 v153, 0xbfb8aa3b, v49
	v_exp_f32_e32 v150, v150
	v_exp_f32_e32 v152, v152
	v_exp_f32_e32 v151, v151
	v_exp_f32_e32 v153, v153
	v_add_f32_e32 v150, 1.0, v150
	v_add_f32_e32 v152, 1.0, v152
	v_add_f32_e32 v151, 1.0, v151
	v_add_f32_e32 v153, 1.0, v153
	v_rcp_f32_e32 v150, v150
	v_rcp_f32_e32 v152, v152
	v_rcp_f32_e32 v151, v151
	v_rcp_f32_e32 v153, v153
	v_pk_mul_f32 v[46:47], v[46:47], v[150:151]
	v_pk_mul_f32 v[48:49], v[48:49], v[152:153]
	v_pk_mul_f32 v[46:47], v[42:43], v[46:47]
	v_pk_mul_f32 v[48:49], v[44:45], v[48:49]
	v_cvt_pk_bf16_f32 v180, v46, v47
	v_cvt_pk_bf16_f32 v181, v48, v49
	v_mul_f32_e32 v154, 0xbfb8aa3b, v38
	v_mul_f32_e32 v156, 0xbfb8aa3b, v40
	v_mul_f32_e32 v155, 0xbfb8aa3b, v39
	v_mul_f32_e32 v157, 0xbfb8aa3b, v41
	v_exp_f32_e32 v154, v154
	v_exp_f32_e32 v156, v156
	v_exp_f32_e32 v155, v155
	v_exp_f32_e32 v157, v157
	v_add_f32_e32 v154, 1.0, v154
	v_add_f32_e32 v156, 1.0, v156
	v_add_f32_e32 v155, 1.0, v155
	v_add_f32_e32 v157, 1.0, v157
	v_rcp_f32_e32 v154, v154
	v_rcp_f32_e32 v156, v156
	v_rcp_f32_e32 v155, v155
	v_rcp_f32_e32 v157, v157
	v_pk_mul_f32 v[38:39], v[38:39], v[154:155]
	v_pk_mul_f32 v[40:41], v[40:41], v[156:157]
	v_pk_mul_f32 v[38:39], v[34:35], v[38:39]
	v_pk_mul_f32 v[40:41], v[36:37], v[40:41]
	v_cvt_pk_bf16_f32 v182, v38, v39
	v_cvt_pk_bf16_f32 v183, v40, v41
	global_store_dwordx4 v[224:225], v[180:183], off nt
	v_mul_f32_e32 v150, 0xbfb8aa3b, v30
	v_mul_f32_e32 v152, 0xbfb8aa3b, v32
	v_mul_f32_e32 v151, 0xbfb8aa3b, v31
	v_mul_f32_e32 v153, 0xbfb8aa3b, v33
	v_exp_f32_e32 v150, v150
	v_exp_f32_e32 v152, v152
	v_exp_f32_e32 v151, v151
	v_exp_f32_e32 v153, v153
	v_add_f32_e32 v150, 1.0, v150
	v_add_f32_e32 v152, 1.0, v152
	v_add_f32_e32 v151, 1.0, v151
	v_add_f32_e32 v153, 1.0, v153
	v_rcp_f32_e32 v150, v150
	v_rcp_f32_e32 v152, v152
	v_rcp_f32_e32 v151, v151
	v_rcp_f32_e32 v153, v153
	v_pk_mul_f32 v[30:31], v[30:31], v[150:151]
	v_pk_mul_f32 v[32:33], v[32:33], v[152:153]
	v_pk_mul_f32 v[30:31], v[26:27], v[30:31]
	v_pk_mul_f32 v[32:33], v[28:29], v[32:33]
	v_cvt_pk_bf16_f32 v184, v30, v31
	v_cvt_pk_bf16_f32 v185, v32, v33
	v_mul_f32_e32 v154, 0xbfb8aa3b, v22
	v_mul_f32_e32 v156, 0xbfb8aa3b, v24
	v_mul_f32_e32 v155, 0xbfb8aa3b, v23
	v_mul_f32_e32 v157, 0xbfb8aa3b, v25
	v_exp_f32_e32 v154, v154
	v_exp_f32_e32 v156, v156
	v_exp_f32_e32 v155, v155
	v_exp_f32_e32 v157, v157
	v_add_f32_e32 v154, 1.0, v154
	v_add_f32_e32 v156, 1.0, v156
	v_add_f32_e32 v155, 1.0, v155
	v_add_f32_e32 v157, 1.0, v157
	v_rcp_f32_e32 v154, v154
	v_rcp_f32_e32 v156, v156
	v_rcp_f32_e32 v155, v155
	v_rcp_f32_e32 v157, v157
	v_pk_mul_f32 v[22:23], v[22:23], v[154:155]
	v_pk_mul_f32 v[24:25], v[24:25], v[156:157]
	v_pk_mul_f32 v[22:23], v[18:19], v[22:23]
	v_pk_mul_f32 v[24:25], v[20:21], v[24:25]
	v_cvt_pk_bf16_f32 v186, v22, v23
	v_cvt_pk_bf16_f32 v187, v24, v25
	global_store_dwordx4 v[226:227], v[184:187], off nt
	v_mul_f32_e32 v150, 0xbfb8aa3b, v14
	v_mul_f32_e32 v152, 0xbfb8aa3b, v16
	v_mul_f32_e32 v151, 0xbfb8aa3b, v15
	v_mul_f32_e32 v153, 0xbfb8aa3b, v17
	v_exp_f32_e32 v150, v150
	v_exp_f32_e32 v152, v152
	v_exp_f32_e32 v151, v151
	v_exp_f32_e32 v153, v153
	v_add_f32_e32 v150, 1.0, v150
	v_add_f32_e32 v152, 1.0, v152
	v_add_f32_e32 v151, 1.0, v151
	v_add_f32_e32 v153, 1.0, v153
	v_rcp_f32_e32 v150, v150
	v_rcp_f32_e32 v152, v152
	v_rcp_f32_e32 v151, v151
	v_rcp_f32_e32 v153, v153
	v_pk_mul_f32 v[14:15], v[14:15], v[150:151]
	v_pk_mul_f32 v[16:17], v[16:17], v[152:153]
	v_pk_mul_f32 v[14:15], v[10:11], v[14:15]
	v_pk_mul_f32 v[16:17], v[12:13], v[16:17]
	v_cvt_pk_bf16_f32 v188, v14, v15
	v_cvt_pk_bf16_f32 v189, v16, v17
	v_mul_f32_e32 v154, 0xbfb8aa3b, v6
	v_mul_f32_e32 v156, 0xbfb8aa3b, v8
	v_mul_f32_e32 v155, 0xbfb8aa3b, v7
	v_mul_f32_e32 v157, 0xbfb8aa3b, v9
	v_exp_f32_e32 v154, v154
	v_exp_f32_e32 v156, v156
	v_exp_f32_e32 v155, v155
	v_exp_f32_e32 v157, v157
	v_add_f32_e32 v154, 1.0, v154
	v_add_f32_e32 v156, 1.0, v156
	v_add_f32_e32 v155, 1.0, v155
	v_add_f32_e32 v157, 1.0, v157
	v_rcp_f32_e32 v154, v154
	v_rcp_f32_e32 v156, v156
	v_rcp_f32_e32 v155, v155
	v_rcp_f32_e32 v157, v157
	v_pk_mul_f32 v[6:7], v[6:7], v[154:155]
	v_pk_mul_f32 v[8:9], v[8:9], v[156:157]
	v_pk_mul_f32 v[6:7], v[2:3], v[6:7]
	v_pk_mul_f32 v[8:9], v[4:5], v[8:9]
	v_cvt_pk_bf16_f32 v190, v6, v7
	v_cvt_pk_bf16_f32 v191, v8, v9
	global_store_dwordx4 v[236:237], v[188:191], off nt
	s_cbranch_vccnz .LBB0_278
	s_andn2_b64 vcc, exec, s[14:15]
	s_cbranch_vccnz .LBB0_277
	s_barrier
	s_branch .LBB0_277
